# v15 + W1 relu2 epilogue: drop redundant canonicalizing v_max (keeping store-data hazard spacing); attention decide: drop 2 canonicalizing v_max per step
# speedup vs baseline: 1.0055x; 1.0055x over previous
; __device__ __forceinline__ bool att_decide(f32x16& c0, f32x16& c1, float& mhat, float& lrun, float& fsc) {
;     c0 = c0 - mhat; c1 = c1 - mhat;
;     float ra = fmaxf(fmaxf(c0[0], c0[1]), c0[2]), rb = fmaxf(fmaxf(c1[0], c1[1]), c1[2]);
; #pragma unroll
;     for (int r = 3; r < 15; r += 2) { ra = fmaxf(fmaxf(ra, c0[r]), c0[r + 1]); rb = fmaxf(fmaxf(rb, c1[r]), c1[r + 1]); }
;     float rm = fmaxf(fmaxf(ra, rb), fmaxf(c0[15], c1[15]));
;     { auto rr = __builtin_amdgcn_permlane32_swap(__float_as_uint(rm), __float_as_uint(rm), false, false); rm = fmaxf(__uint_as_float(rr[0]), __uint_as_float(rr[1])); }
;     bool resc = false; fsc = 1.f;
;     if (__builtin_expect(__any(rm > ATT_THR), 0)) { asm volatile("; rare: reference update" ::: "memory"); const float dl = fmaxf(rm, 0.f); mhat += dl; fsc = __builtin_amdgcn_exp2f(-dl); lrun *= fsc; c0 = c0 - dl; c1 = c1 - dl; resc = true; }
;     return resc;
.LBB0_769:
	v_mov_b32_e32 v44, v92
	v_mov_b32_e32 v92, v64
	v_mov_b32_e32 v45, v93
	v_max3_f32 v64, v80, v81, v82
	v_max3_f32 v93, v92, v65, v66
	v_max3_f32 v64, v64, v83, v84
	v_max3_f32 v93, v93, v67, v68
	v_max3_f32 v64, v64, v85, v86
	v_max3_f32 v93, v93, v69, v70
	v_max3_f32 v64, v64, v87, v88
	v_max3_f32 v93, v93, v71, v72
	v_max3_f32 v64, v64, v89, v90
	v_max3_f32 v93, v93, v73, v74
	v_mov_b32_e32 v47, v95
	v_mov_b32_e32 v46, v94
	v_max3_f32 v64, v64, v91, v44
	v_max3_f32 v93, v93, v75, v76
	v_max3_f32 v64, v64, v45, v46
	v_max3_f32 v93, v93, v77, v78
	v_max_f32_e32 v94, v47, v79
	v_max3_f32 v64, v64, v93, v94
	v_mov_b32_e32 v93, v64
	s_nop 1
	v_permlane32_swap_b32_e32 v64, v93
	v_max_f32_e32 v64, v64, v93
	v_cmp_lt_f32_e32 vcc, s67, v64
	s_cmp_lg_u64 vcc, 0
	s_cselect_b64 s[62:63], -1, 0
	s_cbranch_vccnz .LBB0_814
	v_mov_b32_e32 v64, 1.0

; __device__ __forceinline__ bool att_decide(f32x16& c0, f32x16& c1, float& mhat, float& lrun, float& fsc) {
;     c0 = c0 - mhat; c1 = c1 - mhat;
;     float ra = fmaxf(fmaxf(c0[0], c0[1]), c0[2]), rb = fmaxf(fmaxf(c1[0], c1[1]), c1[2]);
; #pragma unroll
;     for (int r = 3; r < 15; r += 2) { ra = fmaxf(fmaxf(ra, c0[r]), c0[r + 1]); rb = fmaxf(fmaxf(rb, c1[r]), c1[r + 1]); }
;     float rm = fmaxf(fmaxf(ra, rb), fmaxf(c0[15], c1[15]));
;     { auto rr = __builtin_amdgcn_permlane32_swap(__float_as_uint(rm), __float_as_uint(rm), false, false); rm = fmaxf(__uint_as_float(rr[0]), __uint_as_float(rr[1])); }
;     bool resc = false; fsc = 1.f;
;     if (__builtin_expect(__any(rm > ATT_THR), 0)) { asm volatile("; rare: reference update" ::: "memory"); const float dl = fmaxf(rm, 0.f); mhat += dl; fsc = __builtin_amdgcn_exp2f(-dl); lrun *= fsc; c0 = c0 - dl; c1 = c1 - dl; resc = true; }
;     return resc;
.LBB0_835:
	v_mov_b32_e32 v44, v92
	v_mov_b32_e32 v92, v64
	v_mov_b32_e32 v45, v93
	v_max3_f32 v64, v80, v81, v82
	v_max3_f32 v93, v92, v65, v66
	v_max3_f32 v64, v64, v83, v84
	v_max3_f32 v93, v93, v67, v68
	v_max3_f32 v64, v64, v85, v86
	v_max3_f32 v93, v93, v69, v70
	v_max3_f32 v64, v64, v87, v88
	v_max3_f32 v93, v93, v71, v72
	v_max3_f32 v64, v64, v89, v90
	v_max3_f32 v93, v93, v73, v74
	v_mov_b32_e32 v47, v95
	v_mov_b32_e32 v46, v94
	v_max3_f32 v64, v64, v91, v44
	v_max3_f32 v93, v93, v75, v76
	v_max3_f32 v64, v64, v45, v46
	v_max3_f32 v93, v93, v77, v78
	v_max_f32_e32 v94, v47, v79
	v_max3_f32 v64, v64, v93, v94
	v_mov_b32_e32 v93, v64
	s_nop 1
	v_permlane32_swap_b32_e32 v64, v93
	v_max_f32_e32 v64, v64, v93
	v_cmp_lt_f32_e32 vcc, s67, v64
	s_cmp_lg_u64 vcc, 0
	s_cselect_b64 s[34:35], -1, 0
	s_cbranch_vccnz .LBB0_861
	v_mov_b32_e32 v64, 1.0

; __device__ __forceinline__ bool att_decide(f32x16& c0, f32x16& c1, float& mhat, float& lrun, float& fsc) {
;     c0 = c0 - mhat; c1 = c1 - mhat;
;     float ra = fmaxf(fmaxf(c0[0], c0[1]), c0[2]), rb = fmaxf(fmaxf(c1[0], c1[1]), c1[2]);
; #pragma unroll
;     for (int r = 3; r < 15; r += 2) { ra = fmaxf(fmaxf(ra, c0[r]), c0[r + 1]); rb = fmaxf(fmaxf(rb, c1[r]), c1[r + 1]); }
;     float rm = fmaxf(fmaxf(ra, rb), fmaxf(c0[15], c1[15]));
;     { auto rr = __builtin_amdgcn_permlane32_swap(__float_as_uint(rm), __float_as_uint(rm), false, false); rm = fmaxf(__uint_as_float(rr[0]), __uint_as_float(rr[1])); }
;     bool resc = false; fsc = 1.f;
;     if (__builtin_expect(__any(rm > ATT_THR), 0)) { asm volatile("; rare: reference update" ::: "memory"); const float dl = fmaxf(rm, 0.f); mhat += dl; fsc = __builtin_amdgcn_exp2f(-dl); lrun *= fsc; c0 = c0 - dl; c1 = c1 - dl; resc = true; }
;     return resc;
.LBB0_1102:
	v_sub_f32_e32 v66, v116, v250
	v_sub_f32_e32 v65, v115, v250
	v_sub_f32_e32 v64, v114, v250
	v_sub_f32_e32 v84, v100, v250
	v_sub_f32_e32 v83, v99, v250
	v_sub_f32_e32 v82, v98, v250
	v_sub_f32_e32 v68, v118, v250
	v_sub_f32_e32 v67, v117, v250
	v_sub_f32_e32 v86, v102, v250
	v_sub_f32_e32 v85, v101, v250
	v_max3_f32 v80, v64, v65, v66
	v_max3_f32 v81, v82, v83, v84
	v_sub_f32_e32 v70, v120, v250
	v_sub_f32_e32 v69, v119, v250
	v_sub_f32_e32 v88, v104, v250
	v_sub_f32_e32 v87, v103, v250
	v_max3_f32 v80, v80, v67, v68
	v_max3_f32 v81, v81, v85, v86
	v_sub_f32_e32 v72, v122, v250
	v_sub_f32_e32 v71, v121, v250
	v_sub_f32_e32 v90, v106, v250
	v_sub_f32_e32 v89, v105, v250
	v_max3_f32 v80, v80, v69, v70
	v_max3_f32 v81, v81, v87, v88
	v_sub_f32_e32 v74, v124, v250
	v_sub_f32_e32 v73, v123, v250
	v_sub_f32_e32 v92, v108, v250
	v_sub_f32_e32 v91, v107, v250
	v_max3_f32 v80, v80, v71, v72
	v_max3_f32 v81, v81, v89, v90
	v_sub_f32_e32 v76, v126, v250
	v_sub_f32_e32 v75, v125, v250
	v_sub_f32_e32 v94, v110, v250
	v_sub_f32_e32 v93, v109, v250
	v_max3_f32 v80, v80, v73, v74
	v_max3_f32 v81, v81, v91, v92
	v_sub_f32_e32 v79, v129, v250
	v_sub_f32_e32 v78, v128, v250
	v_sub_f32_e32 v77, v127, v250
	v_sub_f32_e32 v97, v113, v250
	v_sub_f32_e32 v96, v112, v250
	v_sub_f32_e32 v95, v111, v250
	v_max3_f32 v80, v80, v75, v76
	v_max3_f32 v81, v81, v93, v94
	v_max3_f32 v80, v80, v77, v78
	v_max3_f32 v81, v81, v95, v96
	v_max_f32_e32 v98, v79, v97
	v_max3_f32 v80, v80, v81, v98
	v_mov_b32_e32 v81, v80
	s_nop 1
	v_permlane32_swap_b32_e32 v80, v81
	v_max_f32_e32 v80, v80, v81
	v_cmp_lt_f32_e32 vcc, s67, v80
	s_cmp_lg_u64 vcc, 0
	s_cselect_b64 s[68:69], -1, 0
	s_cbranch_vccnz .LBB0_1119
	v_mov_b32_e32 v98, 1.0
	s_and_b64 vcc, exec, s[38:39]
	s_cbranch_vccnz .LBB0_1105

; __device__ __forceinline__ bool att_decide(f32x16& c0, f32x16& c1, float& mhat, float& lrun, float& fsc) {
;     c0 = c0 - mhat; c1 = c1 - mhat;
;     float ra = fmaxf(fmaxf(c0[0], c0[1]), c0[2]), rb = fmaxf(fmaxf(c1[0], c1[1]), c1[2]);
; #pragma unroll
;     for (int r = 3; r < 15; r += 2) { ra = fmaxf(fmaxf(ra, c0[r]), c0[r + 1]); rb = fmaxf(fmaxf(rb, c1[r]), c1[r + 1]); }
;     float rm = fmaxf(fmaxf(ra, rb), fmaxf(c0[15], c1[15]));
;     { auto rr = __builtin_amdgcn_permlane32_swap(__float_as_uint(rm), __float_as_uint(rm), false, false); rm = fmaxf(__uint_as_float(rr[0]), __uint_as_float(rr[1])); }
;     bool resc = false; fsc = 1.f;
;     if (__builtin_expect(__any(rm > ATT_THR), 0)) { asm volatile("; rare: reference update" ::: "memory"); const float dl = fmaxf(rm, 0.f); mhat += dl; fsc = __builtin_amdgcn_exp2f(-dl); lrun *= fsc; c0 = c0 - dl; c1 = c1 - dl; resc = true; }
;     return resc;
.LBB0_1127:
	v_sub_f32_e32 v66, v116, v250
	v_sub_f32_e32 v65, v115, v250
	v_sub_f32_e32 v64, v114, v250
	v_sub_f32_e32 v84, v100, v250
	v_sub_f32_e32 v83, v99, v250
	v_sub_f32_e32 v82, v98, v250
	v_sub_f32_e32 v68, v118, v250
	v_sub_f32_e32 v67, v117, v250
	v_sub_f32_e32 v86, v102, v250
	v_sub_f32_e32 v85, v101, v250
	v_max3_f32 v80, v64, v65, v66
	v_max3_f32 v81, v82, v83, v84
	v_sub_f32_e32 v70, v120, v250
	v_sub_f32_e32 v69, v119, v250
	v_sub_f32_e32 v88, v104, v250
	v_sub_f32_e32 v87, v103, v250
	v_max3_f32 v80, v80, v67, v68
	v_max3_f32 v81, v81, v85, v86
	v_sub_f32_e32 v72, v122, v250
	v_sub_f32_e32 v71, v121, v250
	v_sub_f32_e32 v90, v106, v250
	v_sub_f32_e32 v89, v105, v250
	v_max3_f32 v80, v80, v69, v70
	v_max3_f32 v81, v81, v87, v88
	v_sub_f32_e32 v74, v124, v250
	v_sub_f32_e32 v73, v123, v250
	v_sub_f32_e32 v92, v108, v250
	v_sub_f32_e32 v91, v107, v250
	v_max3_f32 v80, v80, v71, v72
	v_max3_f32 v81, v81, v89, v90
	v_sub_f32_e32 v76, v126, v250
	v_sub_f32_e32 v75, v125, v250
	v_sub_f32_e32 v94, v110, v250
	v_sub_f32_e32 v93, v109, v250
	v_max3_f32 v80, v80, v73, v74
	v_max3_f32 v81, v81, v91, v92
	v_sub_f32_e32 v79, v129, v250
	v_sub_f32_e32 v78, v128, v250
	v_sub_f32_e32 v77, v127, v250
	v_sub_f32_e32 v97, v113, v250
	v_sub_f32_e32 v96, v112, v250
	v_sub_f32_e32 v95, v111, v250
	v_max3_f32 v80, v80, v75, v76
	v_max3_f32 v81, v81, v93, v94
	v_max3_f32 v80, v80, v77, v78
	v_max3_f32 v81, v81, v95, v96
	v_max_f32_e32 v98, v79, v97
	v_max3_f32 v80, v80, v81, v98
	v_mov_b32_e32 v81, v80
	s_nop 1
	v_permlane32_swap_b32_e32 v80, v81
	v_max_f32_e32 v80, v80, v81
	v_cmp_lt_f32_e32 vcc, s67, v80
	s_cmp_lg_u64 vcc, 0
	s_cselect_b64 s[48:49], -1, 0
	s_cbranch_vccnz .LBB0_1137
	v_mov_b32_e32 v98, 1.0
	s_and_b64 vcc, exec, s[38:39]
	s_branch .LBB0_1130

; __device__ __forceinline__ u32x4 pk8(f32x4 a, f32x4 b) { u32x4 r; r.x = pk2(a[0], a[1]); r.y = pk2(a[2], a[3]); r.z = pk2(b[0], b[1]); r.w = pk2(b[2], b[3]); return r; }
; #define GEMM_CALL(EPI, gA, gB, gM, gN, gK, gLDA, gLDB, cshift, Eobj) do { \
;         pg8::Gemm gg__{(gA), (gB), (gM), (gN), (gK), (gLDA), (gLDB)}; pg8::StaticOrder so__; so__.init((gM), (gN), G, (int)((blockIdx.x + G - ((cshift) % G)) % G)); \
;         pg8::gemm_phase<EPI, pg8::StaticOrder, true, true>(lds, gg__, so__, (Eobj)); } while (0)
;     __device__ __forceinline__ void operator()(AccRef acc, const pg8::Unit& u, int wr, int wc, int fr, int fq) const {
;         bf16_t* base = O + (size_t)(u.pm * 256 + wr * 64 + fr) * ldc + u.pn * 256 + wc * 32 + 8 * fq;
; #pragma unroll
;         for (int ai = 0; ai < 2; ++ai)
; #pragma unroll
;             for (int m = 0; m < 4; ++m) { bf16_t* rowp = base + (size_t)(ai * 128 + m * 16) * ldc;
; #pragma unroll
;                 for (int bj = 0; bj < 2; ++bj) { f32x4 v0 = acc[ai][bj][m][0], v1 = acc[ai][bj][m][1];
; #pragma unroll
;                     for (int j = 0; j < 4; ++j) { float a = fmaxf(v0[j], 0.f), b = fmaxf(v1[j], 0.f); v0[j] = a * a; v1[j] = b * b; }
;                     *(u32x4*)(rowp + bj * 128) = pk8(v0, v1); } }
;     }
; __global__ void __launch_bounds__(512, 2) fwd_megakernel(Args a) {
;     ...
;         { EpiRelu2 E{BIG, DFF}; GEMM_CALL(EpiRelu2, H, W1T + (size_t)l * D * DFF, nrows, DFF, 1024, 1024, 1024, 0, E); }
.LBB0_1629:
	v_mov_b32_e32 v138, v140
	v_mov_b32_e32 v144, v141
	s_lshl_b32 s53, s84, 8
	s_add_i32 s53, s53, s17
	v_add_u32_e32 v138, s53, v138
	v_ashrrev_i32_e32 v139, 31, v138
	v_lshlrev_b64 v[138:139], 13, v[138:139]
	s_lshl_b32 s58, s82, 8
	v_lshl_add_u64 v[138:139], s[30:31], 0, v[138:139]
	s_ashr_i32 s59, s58, 31
	v_lshl_add_u64 v[138:139], s[58:59], 1, v[138:139]
	s_mov_b32 s53, s60
	v_lshlrev_b32_e32 v144, 3, v144
	v_max_f32_e32 v120, 0, v120
	v_max_f32_e32 v124, 0, v124
	v_max_f32_e32 v121, 0, v121
	v_max_f32_e32 v125, 0, v125
	v_max_f32_e32 v122, 0, v122
	v_max_f32_e32 v126, 0, v126
	v_max_f32_e32 v123, 0, v123
	v_max_f32_e32 v127, 0, v127
	v_lshl_add_u64 v[138:139], v[138:139], 0, s[52:53]
	v_ashrrev_i32_e32 v145, 31, v144
	v_pk_mul_f32 v[120:121], v[120:121], v[120:121]
	v_pk_mul_f32 v[124:125], v[124:125], v[124:125]
	v_pk_mul_f32 v[122:123], v[122:123], v[122:123]
	v_pk_mul_f32 v[126:127], v[126:127], v[126:127]
	v_lshl_add_u64 v[138:139], v[144:145], 1, v[138:139]
	v_cvt_pk_bf16_f32 v120, v120, v121
	v_cvt_pk_bf16_f32 v121, v122, v123
	v_cvt_pk_bf16_f32 v122, v124, v125
	v_cvt_pk_bf16_f32 v123, v126, v127
	v_max_f32_e32 v112, 0, v112
	v_max_f32_e32 v113, 0, v113
	global_store_dwordx4 v[138:139], v[120:123], off
	s_nop 1
	v_pk_mul_f32 v[120:121], v[112:113], v[112:113]
	v_max_f32_e32 v113, v114, v114
	v_max_f32_e32 v112, v118, v118
	v_max_f32_e32 v114, 0, v113
	v_max_f32_e32 v113, v119, v119
	v_max_f32_e32 v116, 0, v116
	v_max_f32_e32 v117, 0, v117
	v_max_f32_e32 v112, 0, v112
	v_max_f32_e32 v113, 0, v113
	v_max_f32_e32 v115, 0, v115
	v_pk_mul_f32 v[116:117], v[116:117], v[116:117]
	v_pk_mul_f32 v[118:119], v[112:113], v[112:113]
	v_pk_mul_f32 v[122:123], v[114:115], v[114:115]
	v_cvt_pk_bf16_f32 v112, v116, v117
	v_cvt_pk_bf16_f32 v113, v118, v119
	v_cvt_pk_bf16_f32 v114, v120, v121
	v_cvt_pk_bf16_f32 v115, v122, v123
	v_max_f32_e32 v104, 0, v104
	v_max_f32_e32 v105, 0, v105
	global_store_dwordx4 v[138:139], v[112:115], off offset:256
	s_nop 1
	v_pk_mul_f32 v[112:113], v[104:105], v[104:105]
	v_max_f32_e32 v105, v106, v106
	v_max_f32_e32 v108, 0, v108
	v_max_f32_e32 v109, 0, v109
	v_max_f32_e32 v104, v110, v110
	v_max_f32_e32 v106, 0, v105
	v_max_f32_e32 v105, v111, v111
	v_pk_mul_f32 v[108:109], v[108:109], v[108:109]
	v_max_f32_e32 v104, 0, v104
	v_max_f32_e32 v105, 0, v105
	v_max_f32_e32 v107, 0, v107
	v_pk_mul_f32 v[110:111], v[104:105], v[104:105]
	v_pk_mul_f32 v[114:115], v[106:107], v[106:107]
	v_cvt_pk_bf16_f32 v104, v108, v109
	v_add_co_u32_e32 v108, vcc, s1, v138
	v_cvt_pk_bf16_f32 v105, v110, v111
	v_cvt_pk_bf16_f32 v106, v112, v113
	v_cvt_pk_bf16_f32 v107, v114, v115
	v_addc_co_u32_e32 v109, vcc, 0, v139, vcc
	v_max_f32_e32 v96, 0, v96
	v_max_f32_e32 v97, 0, v97
	global_store_dwordx4 v[108:109], v[104:107], off
	s_nop 1
	v_pk_mul_f32 v[104:105], v[96:97], v[96:97]
	v_max_f32_e32 v97, v98, v98
	v_max_f32_e32 v96, v102, v102
	v_max_f32_e32 v98, 0, v97
	v_max_f32_e32 v97, v103, v103
	v_max_f32_e32 v100, 0, v100
	v_max_f32_e32 v101, 0, v101
	v_max_f32_e32 v96, 0, v96
	v_max_f32_e32 v97, 0, v97
	v_max_f32_e32 v99, 0, v99
	v_pk_mul_f32 v[100:101], v[100:101], v[100:101]
	v_pk_mul_f32 v[102:103], v[96:97], v[96:97]
	v_pk_mul_f32 v[106:107], v[98:99], v[98:99]
	v_cvt_pk_bf16_f32 v96, v100, v101
	v_cvt_pk_bf16_f32 v97, v102, v103
	v_cvt_pk_bf16_f32 v98, v104, v105
	v_cvt_pk_bf16_f32 v99, v106, v107
	v_max_f32_e32 v88, 0, v88
	v_max_f32_e32 v89, 0, v89
	global_store_dwordx4 v[108:109], v[96:99], off offset:256
	s_nop 1
	v_pk_mul_f32 v[96:97], v[88:89], v[88:89]
	v_max_f32_e32 v89, v90, v90
	v_max_f32_e32 v92, 0, v92
	v_max_f32_e32 v93, 0, v93
	v_max_f32_e32 v88, v94, v94
	v_max_f32_e32 v90, 0, v89
	v_max_f32_e32 v89, v95, v95
	v_pk_mul_f32 v[92:93], v[92:93], v[92:93]
	v_max_f32_e32 v88, 0, v88
	v_max_f32_e32 v89, 0, v89
	v_max_f32_e32 v91, 0, v91
	s_mov_b32 s53, 0x40000
	v_pk_mul_f32 v[94:95], v[88:89], v[88:89]
	v_pk_mul_f32 v[98:99], v[90:91], v[90:91]
	v_cvt_pk_bf16_f32 v88, v92, v93
	v_add_co_u32_e32 v92, vcc, s53, v138
	v_cvt_pk_bf16_f32 v89, v94, v95
	v_cvt_pk_bf16_f32 v90, v96, v97
	v_cvt_pk_bf16_f32 v91, v98, v99
	v_addc_co_u32_e32 v93, vcc, 0, v139, vcc
	v_max_f32_e32 v80, 0, v80
	v_max_f32_e32 v81, 0, v81
	global_store_dwordx4 v[92:93], v[88:91], off
	s_nop 1
	v_pk_mul_f32 v[88:89], v[80:81], v[80:81]
	v_max_f32_e32 v81, v82, v82
	v_max_f32_e32 v80, v86, v86
	v_max_f32_e32 v82, 0, v81
	v_max_f32_e32 v81, v87, v87
	v_max_f32_e32 v84, 0, v84
	v_max_f32_e32 v85, 0, v85
	v_max_f32_e32 v80, 0, v80
	v_max_f32_e32 v81, 0, v81
	v_max_f32_e32 v83, 0, v83
	v_pk_mul_f32 v[84:85], v[84:85], v[84:85]
	v_pk_mul_f32 v[86:87], v[80:81], v[80:81]
	v_pk_mul_f32 v[90:91], v[82:83], v[82:83]
	v_cvt_pk_bf16_f32 v80, v84, v85
	v_cvt_pk_bf16_f32 v81, v86, v87
	v_cvt_pk_bf16_f32 v82, v88, v89
	v_cvt_pk_bf16_f32 v83, v90, v91
	v_max_f32_e32 v72, 0, v72
	v_max_f32_e32 v73, 0, v73
	global_store_dwordx4 v[92:93], v[80:83], off offset:256
	s_nop 1
	v_pk_mul_f32 v[80:81], v[72:73], v[72:73]
	v_max_f32_e32 v73, v74, v74
	v_max_f32_e32 v76, 0, v76
	v_max_f32_e32 v77, 0, v77
	v_max_f32_e32 v72, v78, v78
	v_max_f32_e32 v74, 0, v73
	v_max_f32_e32 v73, v79, v79
	v_pk_mul_f32 v[76:77], v[76:77], v[76:77]
	v_max_f32_e32 v72, 0, v72
	v_max_f32_e32 v73, 0, v73
	v_max_f32_e32 v75, 0, v75
	s_mov_b32 s53, 0x60000
	v_pk_mul_f32 v[78:79], v[72:73], v[72:73]
	v_pk_mul_f32 v[82:83], v[74:75], v[74:75]
	v_cvt_pk_bf16_f32 v72, v76, v77
	v_add_co_u32_e32 v76, vcc, s53, v138
	v_cvt_pk_bf16_f32 v73, v78, v79
	v_cvt_pk_bf16_f32 v74, v80, v81
	v_cvt_pk_bf16_f32 v75, v82, v83
	v_addc_co_u32_e32 v77, vcc, 0, v139, vcc
	v_max_f32_e32 v64, 0, v64
	v_max_f32_e32 v65, 0, v65
; __device__ __forceinline__ u32x4 pk8(f32x4 a, f32x4 b) { u32x4 r; r.x = pk2(a[0], a[1]); r.y = pk2(a[2], a[3]); r.z = pk2(b[0], b[1]); r.w = pk2(b[2], b[3]); return r; }
; #define GEMM_CALL(EPI, gA, gB, gM, gN, gK, gLDA, gLDB, cshift, Eobj) do { \
;         pg8::Gemm gg__{(gA), (gB), (gM), (gN), (gK), (gLDA), (gLDB)}; pg8::StaticOrder so__; so__.init((gM), (gN), G, (int)((blockIdx.x + G - ((cshift) % G)) % G)); \
;         pg8::gemm_phase<EPI, pg8::StaticOrder, true, true>(lds, gg__, so__, (Eobj)); } while (0)
;     __device__ __forceinline__ void operator()(AccRef acc, const pg8::Unit& u, int wr, int wc, int fr, int fq) const {
;         bf16_t* base = O + (size_t)(u.pm * 256 + wr * 64 + fr) * ldc + u.pn * 256 + wc * 32 + 8 * fq;
; #pragma unroll
;         for (int ai = 0; ai < 2; ++ai)
; #pragma unroll
;             for (int m = 0; m < 4; ++m) { bf16_t* rowp = base + (size_t)(ai * 128 + m * 16) * ldc;
; #pragma unroll
;                 for (int bj = 0; bj < 2; ++bj) { f32x4 v0 = acc[ai][bj][m][0], v1 = acc[ai][bj][m][1];
; #pragma unroll
;                     for (int j = 0; j < 4; ++j) { float a = fmaxf(v0[j], 0.f), b = fmaxf(v1[j], 0.f); v0[j] = a * a; v1[j] = b * b; }
;                     *(u32x4*)(rowp + bj * 128) = pk8(v0, v1); } }
;     }
; __global__ void __launch_bounds__(512, 2) fwd_megakernel(Args a) {
;     ...
;         { EpiRelu2 E{BIG, DFF}; GEMM_CALL(EpiRelu2, H, W1T + (size_t)l * D * DFF, nrows, DFF, 1024, 1024, 1024, 0, E); }
	global_store_dwordx4 v[76:77], v[72:75], off
	s_nop 1
	v_pk_mul_f32 v[72:73], v[64:65], v[64:65]
	v_max_f32_e32 v65, v66, v66
	v_max_f32_e32 v64, v70, v70
	v_max_f32_e32 v66, 0, v65
	v_max_f32_e32 v65, v71, v71
	v_max_f32_e32 v68, 0, v68
	v_max_f32_e32 v69, 0, v69
	v_max_f32_e32 v64, 0, v64
	v_max_f32_e32 v65, 0, v65
	v_max_f32_e32 v67, 0, v67
	v_pk_mul_f32 v[68:69], v[68:69], v[68:69]
	v_pk_mul_f32 v[70:71], v[64:65], v[64:65]
	v_pk_mul_f32 v[74:75], v[66:67], v[66:67]
	v_cvt_pk_bf16_f32 v64, v68, v69
	v_cvt_pk_bf16_f32 v65, v70, v71
	v_cvt_pk_bf16_f32 v66, v72, v73
	v_cvt_pk_bf16_f32 v67, v74, v75
	v_max_f32_e32 v56, 0, v56
	v_max_f32_e32 v57, 0, v57
	global_store_dwordx4 v[76:77], v[64:67], off offset:256
	s_nop 1
	v_pk_mul_f32 v[64:65], v[56:57], v[56:57]
	v_max_f32_e32 v57, v58, v58
	v_max_f32_e32 v60, 0, v60
	v_max_f32_e32 v61, 0, v61
	v_max_f32_e32 v56, v62, v62
	v_max_f32_e32 v58, 0, v57
	v_max_f32_e32 v57, v63, v63
	v_pk_mul_f32 v[60:61], v[60:61], v[60:61]
	v_max_f32_e32 v56, 0, v56
	v_max_f32_e32 v57, 0, v57
	v_max_f32_e32 v59, 0, v59
	s_mov_b32 s53, 0x100000
	v_pk_mul_f32 v[62:63], v[56:57], v[56:57]
	v_pk_mul_f32 v[66:67], v[58:59], v[58:59]
	v_cvt_pk_bf16_f32 v56, v60, v61
	v_add_co_u32_e32 v60, vcc, s53, v138
	v_cvt_pk_bf16_f32 v57, v62, v63
	v_cvt_pk_bf16_f32 v58, v64, v65
	v_cvt_pk_bf16_f32 v59, v66, v67
	v_addc_co_u32_e32 v61, vcc, 0, v139, vcc
	v_max_f32_e32 v48, 0, v48
	v_max_f32_e32 v49, 0, v49
	global_store_dwordx4 v[60:61], v[56:59], off
	s_nop 1
	v_pk_mul_f32 v[56:57], v[48:49], v[48:49]
	v_max_f32_e32 v49, v50, v50
	v_max_f32_e32 v48, v54, v54
	v_max_f32_e32 v50, 0, v49
	v_max_f32_e32 v49, v55, v55
	v_max_f32_e32 v52, 0, v52
	v_max_f32_e32 v53, 0, v53
	v_max_f32_e32 v48, 0, v48
	v_max_f32_e32 v49, 0, v49
	v_max_f32_e32 v51, 0, v51
	v_pk_mul_f32 v[52:53], v[52:53], v[52:53]
	v_pk_mul_f32 v[54:55], v[48:49], v[48:49]
	v_pk_mul_f32 v[58:59], v[50:51], v[50:51]
	v_cvt_pk_bf16_f32 v48, v52, v53
	v_cvt_pk_bf16_f32 v49, v54, v55
	v_cvt_pk_bf16_f32 v50, v56, v57
	v_cvt_pk_bf16_f32 v51, v58, v59
	v_max_f32_e32 v40, 0, v40
	v_max_f32_e32 v41, 0, v41
	global_store_dwordx4 v[60:61], v[48:51], off offset:256
	s_nop 1
	v_pk_mul_f32 v[48:49], v[40:41], v[40:41]
	v_max_f32_e32 v41, v42, v42
	v_max_f32_e32 v44, 0, v44
	v_max_f32_e32 v45, 0, v45
	v_max_f32_e32 v40, v46, v46
	v_max_f32_e32 v42, 0, v41
	v_max_f32_e32 v41, v47, v47
	v_pk_mul_f32 v[44:45], v[44:45], v[44:45]
	v_max_f32_e32 v40, 0, v40
	v_max_f32_e32 v41, 0, v41
	v_max_f32_e32 v43, 0, v43
	s_mov_b32 s53, 0x120000
	v_pk_mul_f32 v[46:47], v[40:41], v[40:41]
	v_pk_mul_f32 v[50:51], v[42:43], v[42:43]
	v_cvt_pk_bf16_f32 v40, v44, v45
	v_add_co_u32_e32 v44, vcc, s53, v138
	v_cvt_pk_bf16_f32 v41, v46, v47
	v_cvt_pk_bf16_f32 v42, v48, v49
	v_cvt_pk_bf16_f32 v43, v50, v51
	v_addc_co_u32_e32 v45, vcc, 0, v139, vcc
	v_max_f32_e32 v32, 0, v32
	v_max_f32_e32 v33, 0, v33
	global_store_dwordx4 v[44:45], v[40:43], off
	s_nop 1
	v_pk_mul_f32 v[40:41], v[32:33], v[32:33]
	v_max_f32_e32 v33, v34, v34
	v_max_f32_e32 v32, v38, v38
	v_max_f32_e32 v34, 0, v33
	v_max_f32_e32 v33, v39, v39
	v_max_f32_e32 v36, 0, v36
	v_max_f32_e32 v37, 0, v37
	v_max_f32_e32 v32, 0, v32
	v_max_f32_e32 v33, 0, v33
	v_max_f32_e32 v35, 0, v35
	v_pk_mul_f32 v[36:37], v[36:37], v[36:37]
	v_pk_mul_f32 v[38:39], v[32:33], v[32:33]
	v_pk_mul_f32 v[42:43], v[34:35], v[34:35]
	v_cvt_pk_bf16_f32 v32, v36, v37
	v_cvt_pk_bf16_f32 v33, v38, v39
	v_cvt_pk_bf16_f32 v34, v40, v41
	v_cvt_pk_bf16_f32 v35, v42, v43
	v_max_f32_e32 v24, 0, v24
	v_max_f32_e32 v25, 0, v25
	global_store_dwordx4 v[44:45], v[32:35], off offset:256
	s_nop 1
	v_pk_mul_f32 v[32:33], v[24:25], v[24:25]
	v_max_f32_e32 v25, v26, v26
	v_max_f32_e32 v28, 0, v28
	v_max_f32_e32 v29, 0, v29
	v_max_f32_e32 v24, v30, v30
	v_max_f32_e32 v26, 0, v25
	v_max_f32_e32 v25, v31, v31
	v_pk_mul_f32 v[28:29], v[28:29], v[28:29]
	v_max_f32_e32 v24, 0, v24
	v_max_f32_e32 v25, 0, v25
	v_max_f32_e32 v27, 0, v27
	s_mov_b32 s53, 0x140000
	v_pk_mul_f32 v[30:31], v[24:25], v[24:25]
	v_pk_mul_f32 v[34:35], v[26:27], v[26:27]
	v_cvt_pk_bf16_f32 v24, v28, v29
	v_add_co_u32_e32 v28, vcc, s53, v138
	v_cvt_pk_bf16_f32 v25, v30, v31
	v_cvt_pk_bf16_f32 v26, v32, v33
	v_cvt_pk_bf16_f32 v27, v34, v35
	v_addc_co_u32_e32 v29, vcc, 0, v139, vcc
	v_max_f32_e32 v16, 0, v16
	v_max_f32_e32 v17, 0, v17
	global_store_dwordx4 v[28:29], v[24:27], off
	s_nop 1
	v_pk_mul_f32 v[24:25], v[16:17], v[16:17]
	v_max_f32_e32 v17, v18, v18
	v_max_f32_e32 v16, v22, v22
	v_max_f32_e32 v18, 0, v17
	v_max_f32_e32 v17, v23, v23
	v_max_f32_e32 v20, 0, v20
	v_max_f32_e32 v21, 0, v21
	v_max_f32_e32 v16, 0, v16
	v_max_f32_e32 v17, 0, v17
	v_max_f32_e32 v19, 0, v19
	v_pk_mul_f32 v[20:21], v[20:21], v[20:21]
	v_pk_mul_f32 v[22:23], v[16:17], v[16:17]
	v_pk_mul_f32 v[26:27], v[18:19], v[18:19]
	v_cvt_pk_bf16_f32 v16, v20, v21
	v_cvt_pk_bf16_f32 v17, v22, v23
	v_cvt_pk_bf16_f32 v18, v24, v25
	v_cvt_pk_bf16_f32 v19, v26, v27
	v_max_f32_e32 v8, 0, v8
	v_max_f32_e32 v9, 0, v9
	global_store_dwordx4 v[28:29], v[16:19], off offset:256
	s_nop 1
	v_pk_mul_f32 v[16:17], v[8:9], v[8:9]
	v_max_f32_e32 v9, v10, v10
	v_max_f32_e32 v12, 0, v12
	v_max_f32_e32 v13, 0, v13
	v_max_f32_e32 v8, v14, v14
	v_max_f32_e32 v10, 0, v9
	v_max_f32_e32 v9, v15, v15
	v_pk_mul_f32 v[12:13], v[12:13], v[12:13]
	v_max_f32_e32 v8, 0, v8
	v_max_f32_e32 v9, 0, v9
	v_max_f32_e32 v11, 0, v11
	s_mov_b32 s53, 0x160000
	v_pk_mul_f32 v[14:15], v[8:9], v[8:9]
	v_pk_mul_f32 v[18:19], v[10:11], v[10:11]
	v_cvt_pk_bf16_f32 v8, v12, v13
	v_add_co_u32_e32 v12, vcc, s53, v138
	v_cvt_pk_bf16_f32 v9, v14, v15
	v_cvt_pk_bf16_f32 v10, v16, v17
	v_cvt_pk_bf16_f32 v11, v18, v19
	v_addc_co_u32_e32 v13, vcc, 0, v139, vcc
	v_max_f32_e32 v0, 0, v0
	v_max_f32_e32 v1, 0, v1
	global_store_dwordx4 v[12:13], v[8:11], off
	s_nop 1
	v_pk_mul_f32 v[8:9], v[0:1], v[0:1]
	v_max_f32_e32 v1, v2, v2
	v_max_f32_e32 v0, v6, v6
	v_max_f32_e32 v2, 0, v1
	v_max_f32_e32 v1, v7, v7
	v_max_f32_e32 v4, 0, v4
	v_max_f32_e32 v5, 0, v5
	v_max_f32_e32 v0, 0, v0
	v_max_f32_e32 v1, 0, v1
	v_max_f32_e32 v3, 0, v3
	v_pk_mul_f32 v[4:5], v[4:5], v[4:5]
	v_pk_mul_f32 v[6:7], v[0:1], v[0:1]
	v_pk_mul_f32 v[10:11], v[2:3], v[2:3]
	v_cvt_pk_bf16_f32 v0, v4, v5
	v_cvt_pk_bf16_f32 v1, v6, v7
	v_cvt_pk_bf16_f32 v2, v8, v9
	v_cvt_pk_bf16_f32 v3, v10, v11
	s_andn2_b64 vcc, exec, s[44:45]
	s_mov_b64 s[44:45], -1
	global_store_dwordx4 v[12:13], v[0:3], off offset:256
	s_cbranch_vccnz .LBB0_1621
	s_andn2_b64 vcc, exec, s[36:37]
	s_cbranch_vccnz .LBB0_1620
	s_barrier
	s_branch .LBB0_1620
